# speedup vs baseline: 1.0445x; 1.0108x over previous
; __device__ __forceinline__ unsigned cvt_pk_bf16(float lo, float hi) { unsigned r; asm volatile("v_cvt_pk_bf16_f32 %0, %1, %2" : "=v"(r) : "v"(lo), "v"(hi)); return r; }
;     __device__ __forceinline__ void operator()(const f32x4 (&acc)[2][2][4][2], const Unit& u, int wr, int wc, int fr, int fq) const {
;     ...
;         for (int ai = 0; ai < 2; ++ai)
; #pragma unroll
;             for (int m = 0; m < 4; ++m) {
;                 const int row = row0 + ai * 128 + m * 16; const float rs = row_rs(ssq, row, fq);
;                 bf16* rowp = base + (size_t)row * ldc + ct;
; #pragma unroll
;                 for (int bj = 0; bj < 2; ++bj) {
;                     f32x4 v0 = acc[ai][bj][m][0] * rs + bv[bj][0], v1 = acc[ai][bj][m][1] * rs + bv[bj][1];
;                     if (isg) {
; #pragma unroll
;                         for (int e = 0; e < 4; ++e) { v0[e] = __builtin_amdgcn_rcpf(1.f + __expf(-v0[e])); v1[e] = __builtin_amdgcn_rcpf(1.f + __expf(-v1[e])); }
;                     }
;                     v4u w; w.x = pg8::cvt_pk_bf16(v0[0], v0[1]); w.y = pg8::cvt_pk_bf16(v0[2], v0[3]); w.z = pg8::cvt_pk_bf16(v1[0], v1[1]); w.w = pg8::cvt_pk_bf16(v1[2], v1[3]);
;                     __builtin_nontemporal_store(w, (v4u*)(rowp + bj * 32));
;                 }
.LBB0_300:
	s_and_b64 s[0:1], s[0:1], exec
	s_cselect_b32 s0, s99, s63
	s_cselect_b32 s1, s98, s96
	v_mov_b32_e32 v140, s1
	v_mov_b32_e32 v141, s0
	v_mov_b32_e32 v165, v164
	v_lshl_add_u64 v[140:141], v[162:163], 1, v[140:141]
	v_mad_i64_i32 v[162:163], s[0:1], s46, v0, 0
	v_cvt_pk_bf16_f32 v144, v144, v145
	v_cvt_pk_bf16_f32 v145, v146, v147
	v_cvt_pk_bf16_f32 v146, v166, v167
	v_cvt_pk_bf16_f32 v147, v142, v143
	v_mov_b32_e32 v142, v164
	v_mov_b32_e32 v143, v164
	v_lshl_add_u64 v[162:163], v[162:163], 1, v[140:141]
	v_pk_fma_f32 v[138:139], v[138:139], v[142:143], v[70:71]
	v_pk_fma_f32 v[136:137], v[136:137], v[164:165], v[68:69]
	v_pk_fma_f32 v[134:135], v[134:135], v[142:143], v[62:63]
	s_and_b64 vcc, exec, s[40:41]
	v_pk_fma_f32 v[132:133], v[132:133], v[164:165], v[60:61]
	global_store_dwordx4 v[162:163], v[144:147], off sc0 sc1 nt
	s_cbranch_vccnz .LBB0_302
	v_mul_f32_e32 v1, 0xbfb8aa3b, v136
	v_exp_f32_e32 v1, v1
	v_mul_f32_e32 v133, 0xbfb8aa3b, v133
	v_exp_f32_e32 v133, v133
	v_mul_f32_e32 v132, 0xbfb8aa3b, v132
	v_add_f32_e32 v1, 1.0, v1
	v_rcp_f32_e32 v136, v1
	v_mul_f32_e32 v1, 0xbfb8aa3b, v137
	v_exp_f32_e32 v1, v1
	v_exp_f32_e32 v132, v132
	v_add_f32_e32 v1, 1.0, v1
	v_rcp_f32_e32 v137, v1
	v_add_f32_e32 v1, 1.0, v133
	v_mul_f32_e32 v133, 0xbfb8aa3b, v138
	v_exp_f32_e32 v138, v133
	v_mul_f32_e32 v133, 0xbfb8aa3b, v134
	v_exp_f32_e32 v134, v133
	v_rcp_f32_e32 v133, v1
	v_add_f32_e32 v1, 1.0, v138
	v_rcp_f32_e32 v138, v1
	v_add_f32_e32 v1, 1.0, v134
	v_mul_f32_e32 v134, 0xbfb8aa3b, v139
	v_exp_f32_e32 v139, v134
	v_mul_f32_e32 v134, 0xbfb8aa3b, v135
	v_exp_f32_e32 v135, v134
	v_rcp_f32_e32 v134, v1
	v_add_f32_e32 v1, 1.0, v139
	v_add_f32_e32 v132, 1.0, v132
	v_rcp_f32_e32 v139, v1
	v_add_f32_e32 v1, 1.0, v135
	v_rcp_f32_e32 v132, v132
	v_rcp_f32_e32 v135, v1
.LBB0_302:
	v_or_b32_e32 v142, 16, v0
	v_ashrrev_i32_e32 v143, 31, v142
	v_cvt_pk_bf16_f32 v136, v136, v137
	v_cvt_pk_bf16_f32 v137, v138, v139
	v_cvt_pk_bf16_f32 v138, v132, v133
	v_lshl_add_u64 v[132:133], s[84:85], 0, v[2:3]
	v_lshlrev_b64 v[144:145], 2, v[142:143]
	v_cvt_pk_bf16_f32 v139, v134, v135
	global_store_dwordx4 v[162:163], v[136:139], off offset:64 sc0 sc1 nt
	v_lshl_add_u64 v[134:135], v[132:133], 0, v[144:145]
	v_lshl_add_u64 v[134:135], s[84:85], 0, v[160:161]
	v_lshl_add_u64 v[136:137], v[134:135], 0, v[144:145]
	v_lshl_add_u64 v[136:137], s[84:85], 0, v[158:159]
	v_lshl_add_u64 v[138:139], v[136:137], 0, v[144:145]
	v_lshl_add_u64 v[138:139], s[84:85], 0, v[156:157]
	v_lshl_add_u64 v[144:145], v[138:139], 0, v[144:145]
	v_fmamk_f32 v1, v178, 0x3a800000, v217
	v_cmp_gt_f32_e32 vcc, s33, v1
	v_mul_f32_e32 v2, 0x4b800000, v1
	s_nop 0
	v_cndmask_b32_e32 v1, v1, v2, vcc
	v_rsq_f32_e32 v1, v1
	s_nop 0
	v_mul_f32_e32 v2, 0x45800000, v1
	v_cndmask_b32_e32 v144, v1, v2, vcc
	v_pk_fma_f32 v[130:131], v[130:131], v[144:145], v[82:83] op_sel_hi:[1,0,1]
	v_pk_fma_f32 v[128:129], v[128:129], v[144:145], v[80:81] op_sel_hi:[1,0,1]
	v_pk_fma_f32 v[126:127], v[126:127], v[144:145], v[78:79] op_sel_hi:[1,0,1]
	v_pk_fma_f32 v[124:125], v[124:125], v[144:145], v[76:77] op_sel_hi:[1,0,1]
	s_and_b64 vcc, exec, s[40:41]
	s_cbranch_vccnz .LBB0_304
	v_mul_f32_e32 v1, 0xbfb8aa3b, v128
	v_exp_f32_e32 v1, v1
	v_mul_f32_e32 v2, 0xbfb8aa3b, v124
	v_exp_f32_e32 v2, v2
	v_mul_f32_e32 v124, 0xbfb8aa3b, v125
	v_add_f32_e32 v1, 1.0, v1
	v_rcp_f32_e32 v128, v1
	v_mul_f32_e32 v1, 0xbfb8aa3b, v129
	v_exp_f32_e32 v1, v1
	v_exp_f32_e32 v125, v124
	v_add_f32_e32 v2, 1.0, v2
	v_rcp_f32_e32 v124, v2
	v_add_f32_e32 v1, 1.0, v1
	v_mul_f32_e32 v2, 0xbfb8aa3b, v130
	v_rcp_f32_e32 v129, v1
	v_add_f32_e32 v1, 1.0, v125
	v_exp_f32_e32 v2, v2
	v_mul_f32_e32 v125, 0xbfb8aa3b, v126
	v_exp_f32_e32 v126, v125
	v_rcp_f32_e32 v125, v1
	v_add_f32_e32 v1, 1.0, v2
	v_mul_f32_e32 v2, 0xbfb8aa3b, v131
	v_rcp_f32_e32 v130, v1
	v_add_f32_e32 v1, 1.0, v126
	v_exp_f32_e32 v2, v2
	v_mul_f32_e32 v126, 0xbfb8aa3b, v127
	v_exp_f32_e32 v127, v126
	v_rcp_f32_e32 v126, v1
	v_add_f32_e32 v1, 1.0, v2
	v_rcp_f32_e32 v131, v1
	v_add_f32_e32 v1, 1.0, v127
	v_rcp_f32_e32 v127, v1
.LBB0_304:
	v_mov_b32_e32 v145, v144
	v_mad_i64_i32 v[142:143], s[0:1], s46, v142, 0
	v_cvt_pk_bf16_f32 v128, v128, v129
	v_cvt_pk_bf16_f32 v129, v130, v131
	v_cvt_pk_bf16_f32 v130, v124, v125
	v_mov_b32_e32 v124, v144
	v_mov_b32_e32 v125, v144
	v_lshl_add_u64 v[142:143], v[142:143], 1, v[140:141]
	v_pk_fma_f32 v[122:123], v[122:123], v[124:125], v[70:71]
	v_pk_fma_f32 v[120:121], v[120:121], v[144:145], v[68:69]
	v_pk_fma_f32 v[118:119], v[118:119], v[124:125], v[62:63]
	s_and_b64 vcc, exec, s[40:41]
	v_pk_fma_f32 v[116:117], v[116:117], v[144:145], v[60:61]
	v_cvt_pk_bf16_f32 v131, v126, v127
	global_store_dwordx4 v[142:143], v[128:131], off sc0 sc1 nt
	s_cbranch_vccnz .LBB0_306
	v_mul_f32_e32 v1, 0xbfb8aa3b, v120
	v_exp_f32_e32 v1, v1
	v_mul_f32_e32 v2, 0xbfb8aa3b, v116
	v_exp_f32_e32 v2, v2
	v_mul_f32_e32 v116, 0xbfb8aa3b, v117
	v_add_f32_e32 v1, 1.0, v1
	v_rcp_f32_e32 v120, v1
	v_mul_f32_e32 v1, 0xbfb8aa3b, v121
	v_exp_f32_e32 v1, v1
	v_exp_f32_e32 v117, v116
	v_add_f32_e32 v2, 1.0, v2
	v_rcp_f32_e32 v116, v2
	v_add_f32_e32 v1, 1.0, v1
	v_mul_f32_e32 v2, 0xbfb8aa3b, v122
	v_rcp_f32_e32 v121, v1
	v_add_f32_e32 v1, 1.0, v117
	v_exp_f32_e32 v2, v2
	v_mul_f32_e32 v117, 0xbfb8aa3b, v118
	v_exp_f32_e32 v118, v117
	v_rcp_f32_e32 v117, v1
	v_add_f32_e32 v1, 1.0, v2
	v_mul_f32_e32 v2, 0xbfb8aa3b, v123
	v_rcp_f32_e32 v122, v1
	v_add_f32_e32 v1, 1.0, v118
	v_exp_f32_e32 v2, v2
	v_mul_f32_e32 v118, 0xbfb8aa3b, v119
	v_exp_f32_e32 v119, v118
	v_rcp_f32_e32 v118, v1
	v_add_f32_e32 v1, 1.0, v2
	v_rcp_f32_e32 v123, v1
	v_add_f32_e32 v1, 1.0, v119
	v_rcp_f32_e32 v119, v1
; __device__ __forceinline__ unsigned cvt_pk_bf16(float lo, float hi) { unsigned r; asm volatile("v_cvt_pk_bf16_f32 %0, %1, %2" : "=v"(r) : "v"(lo), "v"(hi)); return r; }
;     __device__ __forceinline__ void operator()(const f32x4 (&acc)[2][2][4][2], const Unit& u, int wr, int wc, int fr, int fq) const {
;     ...
;                 const int row = row0 + ai * 128 + m * 16; const float rs = row_rs(ssq, row, fq);
;                 bf16* rowp = base + (size_t)row * ldc + ct;
; #pragma unroll
;                 for (int bj = 0; bj < 2; ++bj) {
;                     f32x4 v0 = acc[ai][bj][m][0] * rs + bv[bj][0], v1 = acc[ai][bj][m][1] * rs + bv[bj][1];
;                     if (isg) {
; #pragma unroll
;                         for (int e = 0; e < 4; ++e) { v0[e] = __builtin_amdgcn_rcpf(1.f + __expf(-v0[e])); v1[e] = __builtin_amdgcn_rcpf(1.f + __expf(-v1[e])); }
;                     }
;                     v4u w; w.x = pg8::cvt_pk_bf16(v0[0], v0[1]); w.y = pg8::cvt_pk_bf16(v0[2], v0[3]); w.z = pg8::cvt_pk_bf16(v1[0], v1[1]); w.w = pg8::cvt_pk_bf16(v1[2], v1[3]);
;                     __builtin_nontemporal_store(w, (v4u*)(rowp + bj * 32));
.LBB0_306:
	v_cvt_pk_bf16_f32 v120, v120, v121
	v_cvt_pk_bf16_f32 v121, v122, v123
	v_cvt_pk_bf16_f32 v122, v116, v117
	v_or_b32_e32 v116, 32, v0
	v_ashrrev_i32_e32 v117, 31, v116
	v_cvt_pk_bf16_f32 v123, v118, v119
	v_lshlrev_b64 v[118:119], 2, v[116:117]
	global_store_dwordx4 v[142:143], v[120:123], off offset:64 sc0 sc1 nt
	v_lshl_add_u64 v[124:125], v[136:137], 0, v[118:119]
	s_and_b64 vcc, exec, s[40:41]
	v_lshl_add_u64 v[120:121], v[132:133], 0, v[118:119]
	v_lshl_add_u64 v[122:123], v[134:135], 0, v[118:119]
	v_lshl_add_u64 v[118:119], v[138:139], 0, v[118:119]
	v_fmamk_f32 v1, v182, 0x3a800000, v217
	v_mul_f32_e32 v2, 0x4b800000, v1
	v_cmp_gt_f32_e64 s[0:1], s33, v1
	s_nop 1
	v_cndmask_b32_e64 v1, v1, v2, s[0:1]
	v_rsq_f32_e32 v1, v1
	s_nop 0
	v_mul_f32_e32 v2, 0x45800000, v1
	v_cndmask_b32_e64 v118, v1, v2, s[0:1]
	v_pk_fma_f32 v[114:115], v[114:115], v[118:119], v[82:83] op_sel_hi:[1,0,1]
	v_pk_fma_f32 v[112:113], v[112:113], v[118:119], v[80:81] op_sel_hi:[1,0,1]
	v_pk_fma_f32 v[110:111], v[110:111], v[118:119], v[78:79] op_sel_hi:[1,0,1]
	v_pk_fma_f32 v[120:121], v[108:109], v[118:119], v[76:77] op_sel_hi:[1,0,1]
	s_cbranch_vccnz .LBB0_308
	v_mul_f32_e32 v1, 0xbfb8aa3b, v112
	v_exp_f32_e32 v1, v1
	v_mul_f32_e32 v2, 0xbfb8aa3b, v120
	v_exp_f32_e32 v2, v2
	v_mul_f32_e32 v108, 0xbfb8aa3b, v121
	v_add_f32_e32 v1, 1.0, v1
	v_rcp_f32_e32 v112, v1
	v_mul_f32_e32 v1, 0xbfb8aa3b, v113
	v_exp_f32_e32 v1, v1
	v_exp_f32_e32 v108, v108
	v_add_f32_e32 v2, 1.0, v2
	v_rcp_f32_e32 v120, v2
	v_add_f32_e32 v1, 1.0, v1
	v_mul_f32_e32 v2, 0xbfb8aa3b, v114
	v_rcp_f32_e32 v113, v1
	v_add_f32_e32 v1, 1.0, v108
	v_exp_f32_e32 v2, v2
	v_mul_f32_e32 v108, 0xbfb8aa3b, v110
	v_exp_f32_e32 v108, v108
	v_rcp_f32_e32 v121, v1
	v_add_f32_e32 v1, 1.0, v2
	v_mul_f32_e32 v2, 0xbfb8aa3b, v115
	v_rcp_f32_e32 v114, v1
	v_add_f32_e32 v1, 1.0, v108
	v_exp_f32_e32 v2, v2
	v_mul_f32_e32 v108, 0xbfb8aa3b, v111
	v_exp_f32_e32 v108, v108
	v_rcp_f32_e32 v110, v1
	v_add_f32_e32 v1, 1.0, v2
	v_rcp_f32_e32 v115, v1
	v_add_f32_e32 v1, 1.0, v108
	v_rcp_f32_e32 v111, v1
.LBB0_308:
	v_mov_b32_e32 v119, v118
	v_mad_i64_i32 v[108:109], s[0:1], s46, v116, 0
	v_cvt_pk_bf16_f32 v112, v112, v113
	v_cvt_pk_bf16_f32 v113, v114, v115
	v_cvt_pk_bf16_f32 v114, v120, v121
	v_cvt_pk_bf16_f32 v115, v110, v111
	v_mov_b32_e32 v110, v118
	v_mov_b32_e32 v111, v118
	v_lshl_add_u64 v[108:109], v[108:109], 1, v[140:141]
	v_pk_fma_f32 v[106:107], v[106:107], v[110:111], v[70:71]
	v_pk_fma_f32 v[104:105], v[104:105], v[118:119], v[68:69]
	v_pk_fma_f32 v[102:103], v[102:103], v[110:111], v[62:63]
	s_and_b64 vcc, exec, s[40:41]
	v_pk_fma_f32 v[100:101], v[100:101], v[118:119], v[60:61]
	global_store_dwordx4 v[108:109], v[112:115], off sc0 sc1 nt
	s_cbranch_vccnz .LBB0_310
	v_mul_f32_e32 v1, 0xbfb8aa3b, v104
	v_exp_f32_e32 v1, v1
	v_mul_f32_e32 v2, 0xbfb8aa3b, v100
	v_exp_f32_e32 v2, v2
	v_mul_f32_e32 v100, 0xbfb8aa3b, v101
	v_add_f32_e32 v1, 1.0, v1
	v_rcp_f32_e32 v104, v1
	v_mul_f32_e32 v1, 0xbfb8aa3b, v105
	v_exp_f32_e32 v1, v1
	v_exp_f32_e32 v101, v100
	v_add_f32_e32 v2, 1.0, v2
	v_rcp_f32_e32 v100, v2
	v_add_f32_e32 v1, 1.0, v1
	v_mul_f32_e32 v2, 0xbfb8aa3b, v106
	v_rcp_f32_e32 v105, v1
	v_add_f32_e32 v1, 1.0, v101
	v_exp_f32_e32 v2, v2
	v_mul_f32_e32 v101, 0xbfb8aa3b, v102
	v_exp_f32_e32 v102, v101
	v_rcp_f32_e32 v101, v1
	v_add_f32_e32 v1, 1.0, v2
	v_mul_f32_e32 v2, 0xbfb8aa3b, v107
	v_rcp_f32_e32 v106, v1
	v_add_f32_e32 v1, 1.0, v102
	v_exp_f32_e32 v2, v2
	v_mul_f32_e32 v102, 0xbfb8aa3b, v103
	v_exp_f32_e32 v103, v102
	v_rcp_f32_e32 v102, v1
	v_add_f32_e32 v1, 1.0, v2
	v_rcp_f32_e32 v107, v1
	v_add_f32_e32 v1, 1.0, v103
	v_rcp_f32_e32 v103, v1
.LBB0_310:
	v_cvt_pk_bf16_f32 v104, v104, v105
	v_cvt_pk_bf16_f32 v105, v106, v107
	v_cvt_pk_bf16_f32 v106, v100, v101
	v_or_b32_e32 v100, 48, v0
	v_ashrrev_i32_e32 v101, 31, v100
	v_cvt_pk_bf16_f32 v107, v102, v103
	v_lshlrev_b64 v[102:103], 2, v[100:101]
	global_store_dwordx4 v[108:109], v[104:107], off offset:64 sc0 sc1 nt
	v_lshl_add_u64 v[108:109], v[136:137], 0, v[102:103]
	s_and_b64 vcc, exec, s[40:41]
	v_lshl_add_u64 v[104:105], v[132:133], 0, v[102:103]
	v_lshl_add_u64 v[106:107], v[134:135], 0, v[102:103]
	v_lshl_add_u64 v[102:103], v[138:139], 0, v[102:103]
	v_fmamk_f32 v1, v186, 0x3a800000, v217
	v_mul_f32_e32 v2, 0x4b800000, v1
	v_cmp_gt_f32_e64 s[0:1], s33, v1
	s_nop 1
	v_cndmask_b32_e64 v1, v1, v2, s[0:1]
	v_rsq_f32_e32 v1, v1
	s_nop 0
	v_mul_f32_e32 v2, 0x45800000, v1
	v_cndmask_b32_e64 v102, v1, v2, s[0:1]
	v_pk_fma_f32 v[98:99], v[98:99], v[102:103], v[82:83] op_sel_hi:[1,0,1]
	v_pk_fma_f32 v[96:97], v[96:97], v[102:103], v[80:81] op_sel_hi:[1,0,1]
	v_pk_fma_f32 v[94:95], v[94:95], v[102:103], v[78:79] op_sel_hi:[1,0,1]
	v_pk_fma_f32 v[104:105], v[92:93], v[102:103], v[76:77] op_sel_hi:[1,0,1]
	s_cbranch_vccnz .LBB0_312
	v_mul_f32_e32 v1, 0xbfb8aa3b, v96
	v_exp_f32_e32 v1, v1
	v_mul_f32_e32 v2, 0xbfb8aa3b, v104
	v_exp_f32_e32 v2, v2
	v_mul_f32_e32 v92, 0xbfb8aa3b, v105
	v_add_f32_e32 v1, 1.0, v1
	v_rcp_f32_e32 v96, v1
	v_mul_f32_e32 v1, 0xbfb8aa3b, v97
	v_exp_f32_e32 v1, v1
	v_exp_f32_e32 v92, v92
	v_add_f32_e32 v2, 1.0, v2
	v_rcp_f32_e32 v104, v2
	v_add_f32_e32 v1, 1.0, v1
	v_mul_f32_e32 v2, 0xbfb8aa3b, v98
	v_rcp_f32_e32 v97, v1
	v_add_f32_e32 v1, 1.0, v92
	v_exp_f32_e32 v2, v2
	v_mul_f32_e32 v92, 0xbfb8aa3b, v94
	v_exp_f32_e32 v92, v92
	v_rcp_f32_e32 v105, v1
	v_add_f32_e32 v1, 1.0, v2
	v_mul_f32_e32 v2, 0xbfb8aa3b, v99
	v_rcp_f32_e32 v98, v1
	v_add_f32_e32 v1, 1.0, v92
	v_exp_f32_e32 v2, v2
	v_mul_f32_e32 v92, 0xbfb8aa3b, v95
	v_exp_f32_e32 v92, v92
	v_rcp_f32_e32 v94, v1
	v_add_f32_e32 v1, 1.0, v2
	v_rcp_f32_e32 v99, v1
	v_add_f32_e32 v1, 1.0, v92
	v_rcp_f32_e32 v95, v1
; __device__ __forceinline__ unsigned cvt_pk_bf16(float lo, float hi) { unsigned r; asm volatile("v_cvt_pk_bf16_f32 %0, %1, %2" : "=v"(r) : "v"(lo), "v"(hi)); return r; }
;     __device__ __forceinline__ void operator()(const f32x4 (&acc)[2][2][4][2], const Unit& u, int wr, int wc, int fr, int fq) const {
;     ...
;                 const int row = row0 + ai * 128 + m * 16; const float rs = row_rs(ssq, row, fq);
;                 bf16* rowp = base + (size_t)row * ldc + ct;
; #pragma unroll
;                 for (int bj = 0; bj < 2; ++bj) {
;                     f32x4 v0 = acc[ai][bj][m][0] * rs + bv[bj][0], v1 = acc[ai][bj][m][1] * rs + bv[bj][1];
;                     if (isg) {
; #pragma unroll
;                         for (int e = 0; e < 4; ++e) { v0[e] = __builtin_amdgcn_rcpf(1.f + __expf(-v0[e])); v1[e] = __builtin_amdgcn_rcpf(1.f + __expf(-v1[e])); }
;                     }
;                     v4u w; w.x = pg8::cvt_pk_bf16(v0[0], v0[1]); w.y = pg8::cvt_pk_bf16(v0[2], v0[3]); w.z = pg8::cvt_pk_bf16(v1[0], v1[1]); w.w = pg8::cvt_pk_bf16(v1[2], v1[3]);
;                     __builtin_nontemporal_store(w, (v4u*)(rowp + bj * 32));
.LBB0_312:
	v_mov_b32_e32 v103, v102
	v_mad_i64_i32 v[92:93], s[0:1], s46, v100, 0
	v_cvt_pk_bf16_f32 v96, v96, v97
	v_cvt_pk_bf16_f32 v97, v98, v99
	v_cvt_pk_bf16_f32 v98, v104, v105
	v_cvt_pk_bf16_f32 v99, v94, v95
	v_mov_b32_e32 v94, v102
	v_mov_b32_e32 v95, v102
	v_lshl_add_u64 v[92:93], v[92:93], 1, v[140:141]
	v_pk_fma_f32 v[90:91], v[90:91], v[94:95], v[70:71]
	v_pk_fma_f32 v[88:89], v[88:89], v[102:103], v[68:69]
	v_pk_fma_f32 v[86:87], v[86:87], v[94:95], v[62:63]
	s_and_b64 vcc, exec, s[40:41]
	v_pk_fma_f32 v[84:85], v[84:85], v[102:103], v[60:61]
	global_store_dwordx4 v[92:93], v[96:99], off sc0 sc1 nt
	s_cbranch_vccnz .LBB0_314
	v_mul_f32_e32 v1, 0xbfb8aa3b, v88
	v_exp_f32_e32 v1, v1
	v_mul_f32_e32 v2, 0xbfb8aa3b, v84
	v_exp_f32_e32 v2, v2
	v_mul_f32_e32 v84, 0xbfb8aa3b, v85
	v_add_f32_e32 v1, 1.0, v1
	v_rcp_f32_e32 v88, v1
	v_mul_f32_e32 v1, 0xbfb8aa3b, v89
	v_exp_f32_e32 v1, v1
	v_exp_f32_e32 v85, v84
	v_add_f32_e32 v2, 1.0, v2
	v_rcp_f32_e32 v84, v2
	v_add_f32_e32 v1, 1.0, v1
	v_mul_f32_e32 v2, 0xbfb8aa3b, v90
	v_rcp_f32_e32 v89, v1
	v_add_f32_e32 v1, 1.0, v85
	v_exp_f32_e32 v2, v2
	v_mul_f32_e32 v85, 0xbfb8aa3b, v86
	v_exp_f32_e32 v86, v85
	v_rcp_f32_e32 v85, v1
	v_add_f32_e32 v1, 1.0, v2
	v_mul_f32_e32 v2, 0xbfb8aa3b, v91
	v_rcp_f32_e32 v90, v1
	v_add_f32_e32 v1, 1.0, v86
	v_exp_f32_e32 v2, v2
	v_mul_f32_e32 v86, 0xbfb8aa3b, v87
	v_exp_f32_e32 v87, v86
	v_rcp_f32_e32 v86, v1
	v_add_f32_e32 v1, 1.0, v2
	v_rcp_f32_e32 v91, v1
	v_add_f32_e32 v1, 1.0, v87
	v_rcp_f32_e32 v87, v1
.LBB0_314:
	v_cvt_pk_bf16_f32 v88, v88, v89
	v_cvt_pk_bf16_f32 v89, v90, v91
	v_cvt_pk_bf16_f32 v90, v84, v85
	v_cvt_pk_bf16_f32 v91, v86, v87
	global_store_dwordx4 v[92:93], v[88:91], off offset:64 sc0 sc1 nt
	s_and_b64 vcc, exec, s[40:41]
	v_fmamk_f32 v1, v190, 0x3a800000, v217
	v_mul_f32_e32 v2, 0x4b800000, v1
	v_cmp_gt_f32_e64 s[0:1], s33, v1
	s_nop 1
	v_cndmask_b32_e64 v1, v1, v2, s[0:1]
	v_rsq_f32_e32 v1, v1
	s_nop 0
	v_mul_f32_e32 v2, 0x45800000, v1
	v_cndmask_b32_e64 v84, v1, v2, s[0:1]
	v_pk_fma_f32 v[74:75], v[74:75], v[84:85], v[82:83] op_sel_hi:[1,0,1]
	v_pk_fma_f32 v[72:73], v[72:73], v[84:85], v[80:81] op_sel_hi:[1,0,1]
	v_pk_fma_f32 v[66:67], v[66:67], v[84:85], v[78:79] op_sel_hi:[1,0,1]
	v_pk_fma_f32 v[86:87], v[64:65], v[84:85], v[76:77] op_sel_hi:[1,0,1]
	s_cbranch_vccnz .LBB0_316
	v_mul_f32_e32 v1, 0xbfb8aa3b, v72
	v_exp_f32_e32 v1, v1
	v_mul_f32_e32 v2, 0xbfb8aa3b, v86
	v_exp_f32_e32 v2, v2
	v_mul_f32_e32 v64, 0xbfb8aa3b, v87
	v_add_f32_e32 v1, 1.0, v1
	v_rcp_f32_e32 v72, v1
	v_mul_f32_e32 v1, 0xbfb8aa3b, v73
	v_exp_f32_e32 v1, v1
	v_exp_f32_e32 v64, v64
	v_add_f32_e32 v2, 1.0, v2
	v_rcp_f32_e32 v86, v2
	v_add_f32_e32 v1, 1.0, v1
	v_mul_f32_e32 v2, 0xbfb8aa3b, v74
	v_rcp_f32_e32 v73, v1
	v_add_f32_e32 v1, 1.0, v64
	v_exp_f32_e32 v2, v2
	v_mul_f32_e32 v64, 0xbfb8aa3b, v66
	v_exp_f32_e32 v64, v64
	v_rcp_f32_e32 v87, v1
	v_add_f32_e32 v1, 1.0, v2
	v_mul_f32_e32 v2, 0xbfb8aa3b, v75
	v_rcp_f32_e32 v74, v1
	v_add_f32_e32 v1, 1.0, v64
	v_exp_f32_e32 v2, v2
	v_mul_f32_e32 v64, 0xbfb8aa3b, v67
	v_exp_f32_e32 v64, v64
	v_rcp_f32_e32 v66, v1
	v_add_f32_e32 v1, 1.0, v2
	v_rcp_f32_e32 v75, v1
	v_add_f32_e32 v1, 1.0, v64
	v_rcp_f32_e32 v67, v1
.LBB0_316:
	v_add_u32_e32 v1, 0x80, v0
	v_mov_b32_e32 v85, v84
	v_mad_i64_i32 v[64:65], s[0:1], s46, v1, 0
	v_cvt_pk_bf16_f32 v72, v72, v73
	v_cvt_pk_bf16_f32 v73, v74, v75
	v_cvt_pk_bf16_f32 v74, v86, v87
	v_cvt_pk_bf16_f32 v75, v66, v67
	v_mov_b32_e32 v66, v84
	v_mov_b32_e32 v67, v84
	v_lshl_add_u64 v[64:65], v[64:65], 1, v[140:141]
	v_pk_fma_f32 v[58:59], v[58:59], v[66:67], v[70:71]
	v_pk_fma_f32 v[56:57], v[56:57], v[84:85], v[68:69]
	v_pk_fma_f32 v[54:55], v[54:55], v[66:67], v[62:63]
	s_and_b64 vcc, exec, s[40:41]
	v_pk_fma_f32 v[52:53], v[52:53], v[84:85], v[60:61]
	global_store_dwordx4 v[64:65], v[72:75], off sc0 sc1 nt
	s_cbranch_vccnz .LBB0_318
	v_mul_f32_e32 v1, 0xbfb8aa3b, v56
	v_exp_f32_e32 v1, v1
	v_mul_f32_e32 v2, 0xbfb8aa3b, v52
	v_exp_f32_e32 v2, v2
	v_mul_f32_e32 v52, 0xbfb8aa3b, v53
	v_add_f32_e32 v1, 1.0, v1
	v_rcp_f32_e32 v56, v1
	v_mul_f32_e32 v1, 0xbfb8aa3b, v57
	v_exp_f32_e32 v1, v1
	v_exp_f32_e32 v53, v52
	v_add_f32_e32 v2, 1.0, v2
	v_rcp_f32_e32 v52, v2
	v_add_f32_e32 v1, 1.0, v1
	v_mul_f32_e32 v2, 0xbfb8aa3b, v58
	v_rcp_f32_e32 v57, v1
	v_add_f32_e32 v1, 1.0, v53
	v_exp_f32_e32 v2, v2
	v_mul_f32_e32 v53, 0xbfb8aa3b, v54
	v_exp_f32_e32 v54, v53
	v_rcp_f32_e32 v53, v1
	v_add_f32_e32 v1, 1.0, v2
	v_mul_f32_e32 v2, 0xbfb8aa3b, v59
	v_rcp_f32_e32 v58, v1
	v_add_f32_e32 v1, 1.0, v54
	v_exp_f32_e32 v2, v2
	v_mul_f32_e32 v54, 0xbfb8aa3b, v55
	v_exp_f32_e32 v55, v54
	v_rcp_f32_e32 v54, v1
	v_add_f32_e32 v1, 1.0, v2
	v_rcp_f32_e32 v59, v1
	v_add_f32_e32 v1, 1.0, v55
	v_rcp_f32_e32 v55, v1
.LBB0_318:
	v_cvt_pk_bf16_f32 v56, v56, v57
	v_cvt_pk_bf16_f32 v57, v58, v59
	v_cvt_pk_bf16_f32 v58, v52, v53
	v_cvt_pk_bf16_f32 v59, v54, v55
	global_store_dwordx4 v[64:65], v[56:59], off offset:64 sc0 sc1 nt
	s_and_b64 vcc, exec, s[40:41]
	v_fmamk_f32 v1, v206, 0x3a800000, v217
	v_mul_f32_e32 v2, 0x4b800000, v1
	v_cmp_gt_f32_e64 s[0:1], s33, v1
	s_nop 1
	v_cndmask_b32_e64 v1, v1, v2, s[0:1]
	v_rsq_f32_e32 v1, v1
	s_nop 0
	v_mul_f32_e32 v2, 0x45800000, v1
	v_cndmask_b32_e64 v52, v1, v2, s[0:1]
	v_pk_fma_f32 v[50:51], v[50:51], v[52:53], v[82:83] op_sel_hi:[1,0,1]
	v_pk_fma_f32 v[48:49], v[48:49], v[52:53], v[80:81] op_sel_hi:[1,0,1]
	v_pk_fma_f32 v[46:47], v[46:47], v[52:53], v[78:79] op_sel_hi:[1,0,1]
	v_pk_fma_f32 v[54:55], v[44:45], v[52:53], v[76:77] op_sel_hi:[1,0,1]
	s_cbranch_vccnz .LBB0_320
	v_mul_f32_e32 v1, 0xbfb8aa3b, v48
	v_exp_f32_e32 v1, v1
	v_mul_f32_e32 v2, 0xbfb8aa3b, v54
	v_exp_f32_e32 v2, v2
	v_mul_f32_e32 v44, 0xbfb8aa3b, v55
	v_add_f32_e32 v1, 1.0, v1
	v_rcp_f32_e32 v48, v1
	v_mul_f32_e32 v1, 0xbfb8aa3b, v49
	v_exp_f32_e32 v1, v1
	v_exp_f32_e32 v44, v44
	v_add_f32_e32 v2, 1.0, v2
	v_rcp_f32_e32 v54, v2
	v_add_f32_e32 v1, 1.0, v1
	v_mul_f32_e32 v2, 0xbfb8aa3b, v50
	v_rcp_f32_e32 v49, v1
	v_add_f32_e32 v1, 1.0, v44
	v_exp_f32_e32 v2, v2
	v_mul_f32_e32 v44, 0xbfb8aa3b, v46
	v_exp_f32_e32 v44, v44
	v_rcp_f32_e32 v55, v1
	v_add_f32_e32 v1, 1.0, v2
	v_mul_f32_e32 v2, 0xbfb8aa3b, v51
	v_rcp_f32_e32 v50, v1
	v_add_f32_e32 v1, 1.0, v44
	v_exp_f32_e32 v2, v2
	v_mul_f32_e32 v44, 0xbfb8aa3b, v47
	v_exp_f32_e32 v44, v44
	v_rcp_f32_e32 v46, v1
	v_add_f32_e32 v1, 1.0, v2
	v_rcp_f32_e32 v51, v1
	v_add_f32_e32 v1, 1.0, v44
	v_rcp_f32_e32 v47, v1
; __device__ __forceinline__ unsigned cvt_pk_bf16(float lo, float hi) { unsigned r; asm volatile("v_cvt_pk_bf16_f32 %0, %1, %2" : "=v"(r) : "v"(lo), "v"(hi)); return r; }
;     __device__ __forceinline__ void operator()(const f32x4 (&acc)[2][2][4][2], const Unit& u, int wr, int wc, int fr, int fq) const {
;     ...
;                 const int row = row0 + ai * 128 + m * 16; const float rs = row_rs(ssq, row, fq);
;                 bf16* rowp = base + (size_t)row * ldc + ct;
; #pragma unroll
;                 for (int bj = 0; bj < 2; ++bj) {
;                     f32x4 v0 = acc[ai][bj][m][0] * rs + bv[bj][0], v1 = acc[ai][bj][m][1] * rs + bv[bj][1];
;                     if (isg) {
; #pragma unroll
;                         for (int e = 0; e < 4; ++e) { v0[e] = __builtin_amdgcn_rcpf(1.f + __expf(-v0[e])); v1[e] = __builtin_amdgcn_rcpf(1.f + __expf(-v1[e])); }
;                     }
;                     v4u w; w.x = pg8::cvt_pk_bf16(v0[0], v0[1]); w.y = pg8::cvt_pk_bf16(v0[2], v0[3]); w.z = pg8::cvt_pk_bf16(v1[0], v1[1]); w.w = pg8::cvt_pk_bf16(v1[2], v1[3]);
;                     __builtin_nontemporal_store(w, (v4u*)(rowp + bj * 32));
.LBB0_320:
	v_add_u32_e32 v1, 0x90, v0
	v_mov_b32_e32 v53, v52
	v_mad_i64_i32 v[44:45], s[0:1], s46, v1, 0
	v_cvt_pk_bf16_f32 v48, v48, v49
	v_cvt_pk_bf16_f32 v49, v50, v51
	v_cvt_pk_bf16_f32 v50, v54, v55
	v_cvt_pk_bf16_f32 v51, v46, v47
	v_mov_b32_e32 v46, v52
	v_mov_b32_e32 v47, v52
	v_lshl_add_u64 v[44:45], v[44:45], 1, v[140:141]
	v_pk_fma_f32 v[42:43], v[42:43], v[46:47], v[70:71]
	v_pk_fma_f32 v[40:41], v[40:41], v[52:53], v[68:69]
	v_pk_fma_f32 v[38:39], v[38:39], v[46:47], v[62:63]
	s_and_b64 vcc, exec, s[40:41]
	v_pk_fma_f32 v[36:37], v[36:37], v[52:53], v[60:61]
	global_store_dwordx4 v[44:45], v[48:51], off sc0 sc1 nt
	s_cbranch_vccnz .LBB0_322
	v_mul_f32_e32 v1, 0xbfb8aa3b, v40
	v_exp_f32_e32 v1, v1
	v_mul_f32_e32 v2, 0xbfb8aa3b, v36
	v_exp_f32_e32 v2, v2
	v_mul_f32_e32 v36, 0xbfb8aa3b, v37
	v_add_f32_e32 v1, 1.0, v1
	v_rcp_f32_e32 v40, v1
	v_mul_f32_e32 v1, 0xbfb8aa3b, v41
	v_exp_f32_e32 v1, v1
	v_exp_f32_e32 v37, v36
	v_add_f32_e32 v2, 1.0, v2
	v_rcp_f32_e32 v36, v2
	v_add_f32_e32 v1, 1.0, v1
	v_mul_f32_e32 v2, 0xbfb8aa3b, v42
	v_rcp_f32_e32 v41, v1
	v_add_f32_e32 v1, 1.0, v37
	v_exp_f32_e32 v2, v2
	v_mul_f32_e32 v37, 0xbfb8aa3b, v38
	v_exp_f32_e32 v38, v37
	v_rcp_f32_e32 v37, v1
	v_add_f32_e32 v1, 1.0, v2
	v_mul_f32_e32 v2, 0xbfb8aa3b, v43
	v_rcp_f32_e32 v42, v1
	v_add_f32_e32 v1, 1.0, v38
	v_exp_f32_e32 v2, v2
	v_mul_f32_e32 v38, 0xbfb8aa3b, v39
	v_exp_f32_e32 v39, v38
	v_rcp_f32_e32 v38, v1
	v_add_f32_e32 v1, 1.0, v2
	v_rcp_f32_e32 v43, v1
	v_add_f32_e32 v1, 1.0, v39
	v_rcp_f32_e32 v39, v1
.LBB0_322:
	v_cvt_pk_bf16_f32 v40, v40, v41
	v_cvt_pk_bf16_f32 v41, v42, v43
	v_cvt_pk_bf16_f32 v42, v36, v37
	v_cvt_pk_bf16_f32 v43, v38, v39
	global_store_dwordx4 v[44:45], v[40:43], off offset:64 sc0 sc1 nt
	s_and_b64 vcc, exec, s[40:41]
	v_fmamk_f32 v1, v210, 0x3a800000, v217
	v_mul_f32_e32 v2, 0x4b800000, v1
	v_cmp_gt_f32_e64 s[0:1], s33, v1
	s_nop 1
	v_cndmask_b32_e64 v1, v1, v2, s[0:1]
	v_rsq_f32_e32 v1, v1
	s_nop 0
	v_mul_f32_e32 v2, 0x45800000, v1
	v_cndmask_b32_e64 v36, v1, v2, s[0:1]
	v_pk_fma_f32 v[34:35], v[34:35], v[36:37], v[82:83] op_sel_hi:[1,0,1]
	v_pk_fma_f32 v[32:33], v[32:33], v[36:37], v[80:81] op_sel_hi:[1,0,1]
	v_pk_fma_f32 v[30:31], v[30:31], v[36:37], v[78:79] op_sel_hi:[1,0,1]
	v_pk_fma_f32 v[38:39], v[28:29], v[36:37], v[76:77] op_sel_hi:[1,0,1]
	s_cbranch_vccnz .LBB0_324
	v_mul_f32_e32 v1, 0xbfb8aa3b, v32
	v_exp_f32_e32 v1, v1
	v_mul_f32_e32 v2, 0xbfb8aa3b, v38
	v_exp_f32_e32 v2, v2
	v_mul_f32_e32 v28, 0xbfb8aa3b, v39
	v_add_f32_e32 v1, 1.0, v1
	v_rcp_f32_e32 v32, v1
	v_mul_f32_e32 v1, 0xbfb8aa3b, v33
	v_exp_f32_e32 v1, v1
	v_exp_f32_e32 v28, v28
	v_add_f32_e32 v2, 1.0, v2
	v_rcp_f32_e32 v38, v2
	v_add_f32_e32 v1, 1.0, v1
	v_mul_f32_e32 v2, 0xbfb8aa3b, v34
	v_rcp_f32_e32 v33, v1
	v_add_f32_e32 v1, 1.0, v28
	v_exp_f32_e32 v2, v2
	v_mul_f32_e32 v28, 0xbfb8aa3b, v30
	v_exp_f32_e32 v28, v28
	v_rcp_f32_e32 v39, v1
	v_add_f32_e32 v1, 1.0, v2
	v_mul_f32_e32 v2, 0xbfb8aa3b, v35
	v_rcp_f32_e32 v34, v1
	v_add_f32_e32 v1, 1.0, v28
	v_exp_f32_e32 v2, v2
	v_mul_f32_e32 v28, 0xbfb8aa3b, v31
	v_exp_f32_e32 v28, v28
	v_rcp_f32_e32 v30, v1
	v_add_f32_e32 v1, 1.0, v2
	v_rcp_f32_e32 v35, v1
	v_add_f32_e32 v1, 1.0, v28
	v_rcp_f32_e32 v31, v1
.LBB0_324:
	v_add_u32_e32 v1, 0xa0, v0
	v_mov_b32_e32 v37, v36
	v_mad_i64_i32 v[28:29], s[0:1], s46, v1, 0
	v_cvt_pk_bf16_f32 v32, v32, v33
	v_cvt_pk_bf16_f32 v33, v34, v35
	v_cvt_pk_bf16_f32 v34, v38, v39
	v_cvt_pk_bf16_f32 v35, v30, v31
	v_mov_b32_e32 v30, v36
	v_mov_b32_e32 v31, v36
	v_lshl_add_u64 v[28:29], v[28:29], 1, v[140:141]
	v_pk_fma_f32 v[26:27], v[26:27], v[30:31], v[70:71]
	v_pk_fma_f32 v[24:25], v[24:25], v[36:37], v[68:69]
	v_pk_fma_f32 v[22:23], v[22:23], v[30:31], v[62:63]
	s_and_b64 vcc, exec, s[40:41]
	v_pk_fma_f32 v[20:21], v[20:21], v[36:37], v[60:61]
	global_store_dwordx4 v[28:29], v[32:35], off sc0 sc1 nt
	s_cbranch_vccnz .LBB0_326
	v_mul_f32_e32 v1, 0xbfb8aa3b, v24
	v_exp_f32_e32 v1, v1
	v_mul_f32_e32 v2, 0xbfb8aa3b, v20
	v_exp_f32_e32 v2, v2
	v_mul_f32_e32 v20, 0xbfb8aa3b, v21
	v_add_f32_e32 v1, 1.0, v1
	v_rcp_f32_e32 v24, v1
	v_mul_f32_e32 v1, 0xbfb8aa3b, v25
	v_exp_f32_e32 v1, v1
	v_exp_f32_e32 v21, v20
	v_add_f32_e32 v2, 1.0, v2
	v_rcp_f32_e32 v20, v2
	v_add_f32_e32 v1, 1.0, v1
	v_mul_f32_e32 v2, 0xbfb8aa3b, v26
	v_rcp_f32_e32 v25, v1
	v_add_f32_e32 v1, 1.0, v21
	v_exp_f32_e32 v2, v2
	v_mul_f32_e32 v21, 0xbfb8aa3b, v22
	v_exp_f32_e32 v22, v21
	v_rcp_f32_e32 v21, v1
	v_add_f32_e32 v1, 1.0, v2
	v_mul_f32_e32 v2, 0xbfb8aa3b, v27
	v_rcp_f32_e32 v26, v1
	v_add_f32_e32 v1, 1.0, v22
	v_exp_f32_e32 v2, v2
	v_mul_f32_e32 v22, 0xbfb8aa3b, v23
	v_exp_f32_e32 v23, v22
	v_rcp_f32_e32 v22, v1
	v_add_f32_e32 v1, 1.0, v2
	v_rcp_f32_e32 v27, v1
	v_add_f32_e32 v1, 1.0, v23
	v_rcp_f32_e32 v23, v1
; __device__ __forceinline__ unsigned cvt_pk_bf16(float lo, float hi) { unsigned r; asm volatile("v_cvt_pk_bf16_f32 %0, %1, %2" : "=v"(r) : "v"(lo), "v"(hi)); return r; }
; #define PG8_BAR __builtin_amdgcn_s_barrier()
; template <class Epi, class Sched, bool ALIGN_EPI = false, bool SP2 = false, bool HALFK = false>
; __device__ __forceinline__ void gemm_phase(PG8_LAS unsigned char* lds, const Gemm g, const Sched& S, const Epi& E, const int tid) {
;     ...
;         if (!has_next) break;
; #pragma unroll
;         for (int a = 0; a < 2; ++a)
; #pragma unroll
;             for (int b = 0; b < 2; ++b)
; #pragma unroll
;                 for (int m = 0; m < 4; ++m)
; #pragma unroll
;                     for (int n = 0; n < 2; ++n) acc[a][b][m][n] = (f32x4){0.f, 0.f, 0.f, 0.f};
;         cur = nxt; cA = nA; cB = nB; ++ui;
;         if constexpr (ALIGN_EPI) { if (wr == 1) PG8_BAR; }
;     __device__ __forceinline__ void operator()(const f32x4 (&acc)[2][2][4][2], const Unit& u, int wr, int wc, int fr, int fq) const {
;     ...
;                 const int row = row0 + ai * 128 + m * 16; const float rs = row_rs(ssq, row, fq);
;                 bf16* rowp = base + (size_t)row * ldc + ct;
; #pragma unroll
;                 for (int bj = 0; bj < 2; ++bj) {
;                     f32x4 v0 = acc[ai][bj][m][0] * rs + bv[bj][0], v1 = acc[ai][bj][m][1] * rs + bv[bj][1];
;                     if (isg) {
; #pragma unroll
;                         for (int e = 0; e < 4; ++e) { v0[e] = __builtin_amdgcn_rcpf(1.f + __expf(-v0[e])); v1[e] = __builtin_amdgcn_rcpf(1.f + __expf(-v1[e])); }
;                     }
;                     v4u w; w.x = pg8::cvt_pk_bf16(v0[0], v0[1]); w.y = pg8::cvt_pk_bf16(v0[2], v0[3]); w.z = pg8::cvt_pk_bf16(v1[0], v1[1]); w.w = pg8::cvt_pk_bf16(v1[2], v1[3]);
;                     __builtin_nontemporal_store(w, (v4u*)(rowp + bj * 32));
.LBB0_326:
	v_cvt_pk_bf16_f32 v24, v24, v25
	v_cvt_pk_bf16_f32 v25, v26, v27
	v_cvt_pk_bf16_f32 v26, v20, v21
	v_cvt_pk_bf16_f32 v27, v22, v23
	global_store_dwordx4 v[28:29], v[24:27], off offset:64 sc0 sc1 nt
	s_and_b64 vcc, exec, s[40:41]
	v_fmamk_f32 v1, v202, 0x3a800000, v217
	v_mul_f32_e32 v2, 0x4b800000, v1
	v_cmp_gt_f32_e64 s[0:1], s33, v1
	s_nop 1
	v_cndmask_b32_e64 v1, v1, v2, s[0:1]
	v_rsq_f32_e32 v1, v1
	s_nop 0
	v_mul_f32_e32 v2, 0x45800000, v1
	v_cndmask_b32_e64 v20, v1, v2, s[0:1]
	v_pk_fma_f32 v[18:19], v[18:19], v[20:21], v[82:83] op_sel_hi:[1,0,1]
	v_pk_fma_f32 v[16:17], v[16:17], v[20:21], v[80:81] op_sel_hi:[1,0,1]
	v_pk_fma_f32 v[14:15], v[14:15], v[20:21], v[78:79] op_sel_hi:[1,0,1]
	v_pk_fma_f32 v[12:13], v[12:13], v[20:21], v[76:77] op_sel_hi:[1,0,1]
	s_cbranch_vccnz .LBB0_328
	v_mul_f32_e32 v1, 0xbfb8aa3b, v16
	v_exp_f32_e32 v1, v1
	v_mul_f32_e32 v2, 0xbfb8aa3b, v12
	v_exp_f32_e32 v2, v2
	v_mul_f32_e32 v12, 0xbfb8aa3b, v13
	v_add_f32_e32 v1, 1.0, v1
	v_rcp_f32_e32 v16, v1
	v_mul_f32_e32 v1, 0xbfb8aa3b, v17
	v_exp_f32_e32 v1, v1
	v_exp_f32_e32 v13, v12
	v_add_f32_e32 v2, 1.0, v2
	v_rcp_f32_e32 v12, v2
	v_add_f32_e32 v1, 1.0, v1
	v_mul_f32_e32 v2, 0xbfb8aa3b, v18
	v_rcp_f32_e32 v17, v1
	v_add_f32_e32 v1, 1.0, v13
	v_exp_f32_e32 v2, v2
	v_mul_f32_e32 v13, 0xbfb8aa3b, v14
	v_exp_f32_e32 v14, v13
	v_rcp_f32_e32 v13, v1
	v_add_f32_e32 v1, 1.0, v2
	v_mul_f32_e32 v2, 0xbfb8aa3b, v19
	v_rcp_f32_e32 v18, v1
	v_add_f32_e32 v1, 1.0, v14
	v_exp_f32_e32 v2, v2
	v_mul_f32_e32 v14, 0xbfb8aa3b, v15
	v_exp_f32_e32 v15, v14
	v_rcp_f32_e32 v14, v1
	v_add_f32_e32 v1, 1.0, v2
	v_rcp_f32_e32 v19, v1
	v_add_f32_e32 v1, 1.0, v15
	v_rcp_f32_e32 v15, v1
.LBB0_328:
	v_add_u32_e32 v0, 0xb0, v0
	v_mov_b32_e32 v21, v20
	v_mad_i64_i32 v[0:1], s[0:1], s46, v0, 0
	v_cvt_pk_bf16_f32 v16, v16, v17
	v_cvt_pk_bf16_f32 v17, v18, v19
	v_cvt_pk_bf16_f32 v18, v12, v13
	v_mov_b32_e32 v12, v20
	v_mov_b32_e32 v13, v20
	v_lshl_add_u64 v[0:1], v[0:1], 1, v[140:141]
	v_pk_fma_f32 v[10:11], v[10:11], v[12:13], v[70:71]
	v_pk_fma_f32 v[8:9], v[8:9], v[20:21], v[68:69]
	v_pk_fma_f32 v[6:7], v[6:7], v[12:13], v[62:63]
	s_and_b64 vcc, exec, s[40:41]
	v_pk_fma_f32 v[4:5], v[4:5], v[20:21], v[60:61]
	v_cvt_pk_bf16_f32 v19, v14, v15
	global_store_dwordx4 v[0:1], v[16:19], off sc0 sc1 nt
	s_cbranch_vccnz .LBB0_330
	v_mul_f32_e32 v2, 0xbfb8aa3b, v8
	v_exp_f32_e32 v2, v2
	v_mul_f32_e32 v5, 0xbfb8aa3b, v5
	v_exp_f32_e32 v5, v5
	v_mul_f32_e32 v4, 0xbfb8aa3b, v4
	v_add_f32_e32 v2, 1.0, v2
	v_rcp_f32_e32 v8, v2
	v_mul_f32_e32 v2, 0xbfb8aa3b, v9
	v_exp_f32_e32 v2, v2
	v_exp_f32_e32 v4, v4
	v_add_f32_e32 v2, 1.0, v2
	v_rcp_f32_e32 v9, v2
	v_add_f32_e32 v2, 1.0, v5
	v_mul_f32_e32 v5, 0xbfb8aa3b, v10
	v_exp_f32_e32 v10, v5
	v_mul_f32_e32 v5, 0xbfb8aa3b, v6
	v_exp_f32_e32 v6, v5
	v_rcp_f32_e32 v5, v2
	v_add_f32_e32 v2, 1.0, v10
	v_rcp_f32_e32 v10, v2
	v_add_f32_e32 v2, 1.0, v6
	v_mul_f32_e32 v6, 0xbfb8aa3b, v11
	v_exp_f32_e32 v11, v6
	v_mul_f32_e32 v6, 0xbfb8aa3b, v7
	v_exp_f32_e32 v7, v6
	v_rcp_f32_e32 v6, v2
	v_add_f32_e32 v2, 1.0, v11
	v_add_f32_e32 v4, 1.0, v4
	v_rcp_f32_e32 v11, v2
	v_add_f32_e32 v2, 1.0, v7
	v_rcp_f32_e32 v4, v4
	v_rcp_f32_e32 v7, v2
.LBB0_330:
	s_andn2_b64 vcc, exec, s[38:39]
	s_mov_b64 s[0:1], -1
	v_cvt_pk_bf16_f32 v8, v8, v9
	v_cvt_pk_bf16_f32 v9, v10, v11
	v_cvt_pk_bf16_f32 v10, v4, v5
	v_cvt_pk_bf16_f32 v11, v6, v7
	global_store_dwordx4 v[0:1], v[8:11], off offset:64 sc0 sc1 nt
	s_cbranch_vccnz .LBB0_283
	v_readlane_b32 s0, v254, 49
	v_readlane_b32 s1, v254, 50
	s_andn2_b64 vcc, exec, s[0:1]
	s_cbranch_vccnz .LBB0_282
	s_barrier
	s_branch .LBB0_282
